# rec scan: image read-modify-write loads of steps 18-31 issued before the scan so their LDS latency hides under it
# baseline (speedup 1.0000x reference)
.Lrec2_loopB_d0:
	ds_read_b128 v[198:201], v130 offset:0
	ds_read_b128 v[214:217], v130 offset:576
	ds_read_b128 v[202:205], v131 offset:0
	ds_read_b128 v[218:221], v131 offset:576
	ds_read_b128 v[206:209], v130 offset:144
	ds_read_b128 v[222:225], v130 offset:720
	ds_read_b128 v[210:213], v131 offset:144
	s_waitcnt lgkmcnt(14)
	ds_read_b128 v[226:229], v131 offset:720
	s_waitcnt lgkmcnt(6)
	v_mfma_f32_16x16x32_bf16 v[100:103], v[198:201], v[20:23], v[12:15]
	v_mfma_f32_16x16x32_bf16 v[104:107], v[198:201], v[52:55], v[16:19]
	v_mfma_f32_16x16x32_bf16 v[108:111], v[198:201], v[84:87], v[242:245]
	v_mfma_f32_16x16x32_bf16 v[112:115], v[214:217], v[20:23], v[12:15]
	v_mfma_f32_16x16x32_bf16 v[138:141], v[214:217], v[52:55], v[16:19]
	v_mfma_f32_16x16x32_bf16 v[142:145], v[214:217], v[84:87], v[242:245]
	s_waitcnt lgkmcnt(4)
	v_mfma_f32_16x16x32_bf16 v[100:103], v[202:205], v[24:27], v[100:103]
	v_mfma_f32_16x16x32_bf16 v[104:107], v[202:205], v[56:59], v[104:107]
	v_mfma_f32_16x16x32_bf16 v[112:115], v[218:221], v[24:27], v[112:115]
	v_mfma_f32_16x16x32_bf16 v[138:141], v[218:221], v[56:59], v[138:141]
	ds_read_b128 v[198:201], v130 offset:288
	ds_read_b128 v[214:217], v130 offset:864
	ds_read_b128 v[202:205], v131 offset:288
	ds_read_b128 v[218:221], v131 offset:864
	s_waitcnt lgkmcnt(6)
	v_mfma_f32_16x16x32_bf16 v[100:103], v[206:209], v[28:31], v[100:103]
	v_mfma_f32_16x16x32_bf16 v[104:107], v[206:209], v[60:63], v[104:107]
	v_mfma_f32_16x16x32_bf16 v[108:111], v[206:209], v[88:91], v[108:111]
	v_mfma_f32_16x16x32_bf16 v[112:115], v[222:225], v[28:31], v[112:115]
	v_mfma_f32_16x16x32_bf16 v[138:141], v[222:225], v[60:63], v[138:141]
	v_mfma_f32_16x16x32_bf16 v[142:145], v[222:225], v[88:91], v[142:145]
	s_waitcnt lgkmcnt(4)
	v_mfma_f32_16x16x32_bf16 v[100:103], v[210:213], v[32:35], v[100:103]
	v_mfma_f32_16x16x32_bf16 v[104:107], v[210:213], v[64:67], v[104:107]
	v_mfma_f32_16x16x32_bf16 v[112:115], v[226:229], v[32:35], v[112:115]
	v_mfma_f32_16x16x32_bf16 v[138:141], v[226:229], v[64:67], v[138:141]
	ds_read_b128 v[206:209], v130 offset:432
	ds_read_b128 v[222:225], v130 offset:1008
	ds_read_b128 v[210:213], v131 offset:432
	ds_read_b128 v[226:229], v131 offset:1008
	s_waitcnt lgkmcnt(6)
	v_mfma_f32_16x16x32_bf16 v[100:103], v[198:201], v[36:39], v[100:103]
	v_mfma_f32_16x16x32_bf16 v[104:107], v[198:201], v[68:71], v[104:107]
	v_mfma_f32_16x16x32_bf16 v[108:111], v[198:201], v[92:95], v[108:111]
	v_mfma_f32_16x16x32_bf16 v[112:115], v[214:217], v[36:39], v[112:115]
	v_mfma_f32_16x16x32_bf16 v[138:141], v[214:217], v[68:71], v[138:141]
	v_mfma_f32_16x16x32_bf16 v[142:145], v[214:217], v[92:95], v[142:145]
	s_waitcnt lgkmcnt(4)
	v_mfma_f32_16x16x32_bf16 v[100:103], v[202:205], v[40:43], v[100:103]
	v_mfma_f32_16x16x32_bf16 v[104:107], v[202:205], v[72:75], v[104:107]
	v_mfma_f32_16x16x32_bf16 v[112:115], v[218:221], v[40:43], v[112:115]
	v_mfma_f32_16x16x32_bf16 v[138:141], v[218:221], v[72:75], v[138:141]
	s_waitcnt lgkmcnt(2)
	v_mfma_f32_16x16x32_bf16 v[100:103], v[206:209], v[44:47], v[100:103]
	v_mfma_f32_16x16x32_bf16 v[104:107], v[206:209], v[76:79], v[104:107]
	v_mfma_f32_16x16x32_bf16 v[108:111], v[206:209], v[96:99], v[108:111]
	v_mfma_f32_16x16x32_bf16 v[112:115], v[222:225], v[44:47], v[112:115]
	v_mfma_f32_16x16x32_bf16 v[138:141], v[222:225], v[76:79], v[138:141]
	v_mfma_f32_16x16x32_bf16 v[142:145], v[222:225], v[96:99], v[142:145]
	s_waitcnt lgkmcnt(0)
	v_mfma_f32_16x16x32_bf16 v[100:103], v[210:213], v[48:51], v[100:103]
	v_mfma_f32_16x16x32_bf16 v[104:107], v[210:213], v[80:83], v[104:107]
	v_mfma_f32_16x16x32_bf16 v[112:115], v[226:229], v[48:51], v[112:115]
	v_mfma_f32_16x16x32_bf16 v[138:141], v[226:229], v[80:83], v[138:141]
	s_waitcnt lgkmcnt(0)
	s_barrier
	s_waitcnt vmcnt(5)
	ds_write_b128 v134, v[146:149]
	ds_write_b128 v134, v[150:153] offset:4608
	ds_write_b128 v135, v[160:163]
	s_add_i32 s64, s4, -1
	s_mul_i32 s71, s64, 0x30000
	s_add_u32 s38, s60, s71
	s_addc_u32 s39, s61, 0
	s_lshl_b32 s64, s64, 12
	v_add_u32_e32 v136, s64, v195
	ds_read_b128 v[116:119], v136
	s_waitcnt vmcnt(3)
	s_waitcnt lgkmcnt(0)
	v_lshlrev_b32_e32 v136, 16, v116
	v_lshlrev_b32_e32 v137, 16, v8
	v_and_b32_e32 v168, 0xffff0000, v116
	v_and_b32_e32 v169, 0xffff0000, v8
	v_mul_f32_e32 v136, v136, v137
	v_mul_f32_e32 v168, v168, v169
	v_cvt_pk_bf16_f32 v116, v136, v168
	v_lshlrev_b32_e32 v136, 16, v117
	v_lshlrev_b32_e32 v137, 16, v9
	v_and_b32_e32 v168, 0xffff0000, v117
	v_and_b32_e32 v169, 0xffff0000, v9
	v_mul_f32_e32 v136, v136, v137
	v_mul_f32_e32 v168, v168, v169
	v_cvt_pk_bf16_f32 v117, v136, v168
	v_lshlrev_b32_e32 v136, 16, v118
	v_lshlrev_b32_e32 v137, 16, v10
	v_and_b32_e32 v168, 0xffff0000, v118
	v_and_b32_e32 v169, 0xffff0000, v10
	v_mul_f32_e32 v136, v136, v137
	v_mul_f32_e32 v168, v168, v169
	v_cvt_pk_bf16_f32 v118, v136, v168
	v_lshlrev_b32_e32 v136, 16, v119
	v_lshlrev_b32_e32 v137, 16, v11
	v_and_b32_e32 v168, 0xffff0000, v119
	v_and_b32_e32 v169, 0xffff0000, v11
	v_mul_f32_e32 v136, v136, v137
	v_mul_f32_e32 v168, v168, v169
	v_cvt_pk_bf16_f32 v119, v136, v168
	global_store_dwordx4 v255, v[116:119], s[38:39]
	s_add_i32 s64, s4, 0
	s_mul_i32 s71, s64, 0x30000
	s_add_u32 s38, s60, s71
	s_addc_u32 s39, s61, 0
	s_lshl_b32 s64, s64, 12
	global_load_dwordx4 v[8:11], v255, s[38:39]
	s_add_i32 s52, s4, 3
	s_min_u32 s52, s52, 31
	s_lshl_b32 s52, s52, 13
	s_add_u32 s26, s50, s52
	s_addc_u32 s27, s51, 0
	global_load_dwordx4 v[146:149], v154, s[26:27]
	global_load_dwordx4 v[150:153], v155, s[26:27]
	global_load_dwordx4 v[160:163], v159, s[26:27]
	v_exp_f32_e32 v198, v100
	v_exp_f32_e32 v199, v101
	v_exp_f32_e32 v200, v102
	v_exp_f32_e32 v201, v103
	v_exp_f32_e32 v202, v112
	v_exp_f32_e32 v203, v113
	v_exp_f32_e32 v204, v114
	v_exp_f32_e32 v205, v115
	v_exp_f32_e32 v214, v104
	v_add_f32_e32 v198, 1.0, v198
	v_exp_f32_e32 v215, v105
	v_add_f32_e32 v199, 1.0, v199
	v_exp_f32_e32 v216, v106
	v_add_f32_e32 v200, 1.0, v200
	v_exp_f32_e32 v217, v107
	v_add_f32_e32 v201, 1.0, v201
	v_exp_f32_e32 v218, v138
	v_add_f32_e32 v202, 1.0, v202
	v_exp_f32_e32 v219, v139
	v_add_f32_e32 v203, 1.0, v203
	v_exp_f32_e32 v220, v140
	v_add_f32_e32 v204, 1.0, v204
	v_exp_f32_e32 v221, v141
	v_add_f32_e32 v205, 1.0, v205
	v_rcp_f32_e32 v198, v198
	v_add_f32_e32 v214, 1.0, v214
	v_rcp_f32_e32 v199, v199
	v_add_f32_e32 v215, 1.0, v215
	v_rcp_f32_e32 v200, v200
	v_add_f32_e32 v216, 1.0, v216
	v_rcp_f32_e32 v201, v201
	v_add_f32_e32 v217, 1.0, v217
	v_rcp_f32_e32 v202, v202
	v_add_f32_e32 v218, 1.0, v218
	v_rcp_f32_e32 v203, v203
	v_add_f32_e32 v219, 1.0, v219
	v_rcp_f32_e32 v204, v204
	v_add_f32_e32 v220, 1.0, v220
	v_rcp_f32_e32 v205, v205
	v_add_f32_e32 v221, 1.0, v221
	v_mul_f32_e32 v198, v179, v198
	v_mul_f32_e32 v199, v179, v199
	v_mul_f32_e32 v200, v179, v200
	v_mul_f32_e32 v201, v179, v201
	v_mul_f32_e32 v202, v179, v202
	v_mul_f32_e32 v203, v179, v203
	v_mul_f32_e32 v204, v179, v204
	v_mul_f32_e32 v205, v179, v205
	v_exp_f32_e32 v120, v198
	v_exp_f32_e32 v121, v199
	v_exp_f32_e32 v122, v200
	v_exp_f32_e32 v123, v201
	v_exp_f32_e32 v124, v202
	v_exp_f32_e32 v125, v203
	v_exp_f32_e32 v126, v204
	v_exp_f32_e32 v127, v205
	v_fma_f32 v206, -v120, v120, 1.0
	v_fma_f32 v207, -v121, v121, 1.0
	v_fma_f32 v208, -v122, v122, 1.0
	v_fma_f32 v209, -v123, v123, 1.0
	v_fma_f32 v210, -v124, v124, 1.0
	v_fma_f32 v211, -v125, v125, 1.0
	v_fma_f32 v212, -v126, v126, 1.0
	v_fma_f32 v213, -v127, v127, 1.0
	v_max_f32_e32 v206, 0xda24260, v206
	v_max_f32_e32 v207, 0xda24260, v207
	v_max_f32_e32 v208, 0xda24260, v208
	v_max_f32_e32 v209, 0xda24260, v209
	v_max_f32_e32 v210, 0xda24260, v210
	v_max_f32_e32 v211, 0xda24260, v211
	v_max_f32_e32 v212, 0xda24260, v212
	v_max_f32_e32 v213, 0xda24260, v213
	v_mul_f32_e32 v198, v214, v206
	v_mul_f32_e32 v199, v215, v207
	v_mul_f32_e32 v200, v216, v208
	v_mul_f32_e32 v201, v217, v209
	v_mul_f32_e32 v202, v218, v210
	v_mul_f32_e32 v203, v219, v211
	v_mul_f32_e32 v204, v220, v212
	v_mul_f32_e32 v205, v221, v213
	v_mul_f32_e32 v214, v214, v198
	v_mul_f32_e32 v215, v215, v199
	v_mul_f32_e32 v216, v216, v200
	v_mul_f32_e32 v217, v217, v201
	v_mul_f32_e32 v218, v218, v202
	v_mul_f32_e32 v219, v219, v203
	v_mul_f32_e32 v220, v220, v204
	v_mul_f32_e32 v221, v221, v205
	v_rsq_f32_e32 v214, v214
	v_mul_f32_e32 v222, v108, v206
	v_rsq_f32_e32 v215, v215
	v_mul_f32_e32 v223, v109, v207
	v_rsq_f32_e32 v216, v216
	v_mul_f32_e32 v224, v110, v208
	v_rsq_f32_e32 v217, v217
	v_mul_f32_e32 v225, v111, v209
	v_rsq_f32_e32 v218, v218
	v_mul_f32_e32 v226, v142, v210
	v_rsq_f32_e32 v219, v219
	v_mul_f32_e32 v227, v143, v211
	v_rsq_f32_e32 v220, v220
	v_mul_f32_e32 v228, v144, v212
	v_rsq_f32_e32 v221, v221
	v_mul_f32_e32 v229, v145, v213
	v_mul_f32_e32 v170, v222, v214
	v_mul_f32_e32 v171, v223, v215
	v_mul_f32_e32 v172, v224, v216
	v_mul_f32_e32 v173, v225, v217
	v_mul_f32_e32 v174, v226, v218
	v_mul_f32_e32 v175, v227, v219
	v_mul_f32_e32 v176, v228, v220
	v_mul_f32_e32 v177, v229, v221
	s_add_i32 s52, s4, 0
	s_lshl_b32 s52, s52, 12
	v_add_u32_e32 v197, s52, v184
	ds_read_u16 v206, v197 offset:0
	ds_read_u16 v207, v197 offset:64
	ds_read_u16 v208, v197 offset:128
	ds_read_u16 v209, v197 offset:192
	ds_read_u16 v210, v197 offset:256
	ds_read_u16 v211, v197 offset:320
	ds_read_u16 v212, v197 offset:384
	ds_read_u16 v213, v197 offset:448
	v_mov_b32_e32 v198, v170
	v_mov_b32_e32 v199, v120
	v_fma_f32 v198, v121, v198, v171
	v_mul_f32_e32 v199, v199, v121
	v_fma_f32 v198, v122, v198, v172
	v_mul_f32_e32 v199, v199, v122
	v_fma_f32 v198, v123, v198, v173
	v_mul_f32_e32 v199, v199, v123
	v_fma_f32 v198, v124, v198, v174
	v_mul_f32_e32 v199, v199, v124
	v_fma_f32 v198, v125, v198, v175
	v_mul_f32_e32 v199, v199, v125
	v_fma_f32 v198, v126, v198, v176
	v_mul_f32_e32 v199, v199, v126
	v_fma_f32 v198, v127, v198, v177
	v_mul_f32_e32 v199, v199, v127
	v_mov_b32_e32 v164, v199
	v_mov_b32_e32 v166, v199
	v_mov_b32_e32 v246, v198
	v_mov_b32_e32 v248, v198
	s_nop 1
	v_permlane32_swap_b32 v164, v166
	v_permlane32_swap_b32 v246, v248
	s_nop 1
	v_mov_b32_e32 v165, v164
	v_mov_b32_e32 v167, v166
	v_mov_b32_e32 v247, v246
	v_mov_b32_e32 v249, v248
	s_nop 1
	v_permlane16_swap_b32 v164, v165
	v_permlane16_swap_b32 v166, v167
	v_permlane16_swap_b32 v246, v247
	v_permlane16_swap_b32 v248, v249
	s_nop 1
	v_mov_b32_e32 v251, v246
	v_mov_b32_e32 v250, v164
	v_fma_f32 v251, v251, v165, v247
	v_mul_f32_e32 v250, v250, v165
	v_fma_f32 v251, v251, v166, v248
	v_mul_f32_e32 v250, v250, v166
	v_fma_f32 v251, v251, v167, v249
	v_mul_f32_e32 v250, v250, v167
	s_mov_b64 exec, s[10:11]
	ds_write_b64 v182, v[250:251] offset:0
	s_mov_b64 exec, -1
	s_waitcnt lgkmcnt(0)
	s_barrier
	ds_read2_b64 v[4:7], v183 offset0:0 offset1:16
	s_add_i32 s52, s4, 0
	s_lshl_b32 s52, s52, 12
	v_add_u32_e32 v197, s52, v184
	s_waitcnt lgkmcnt(0)
	v_fma_f32 v198, v180, v4, v5
	v_cndmask_b32_e64 v199, v180, v198, s[24:25]
	v_fma_f32 v180, v198, v6, v7
	v_fma_f32 v200, v199, v164, v246
	v_cndmask_b32_e64 v199, v199, v200, s[16:17]
	v_fma_f32 v200, v199, v165, v247
	v_cndmask_b32_e64 v199, v199, v200, s[20:21]
	v_fma_f32 v200, v199, v166, v248
	v_cndmask_b32_e64 v199, v199, v200, s[22:23]
	v_fma_f32 v214, v120, v199, v170
	v_fma_f32 v215, v121, v214, v171
	v_fma_f32 v216, v122, v215, v172
	v_fma_f32 v217, v123, v216, v173
	v_fma_f32 v218, v124, v217, v174
	v_fma_f32 v219, v125, v218, v175
	v_fma_f32 v220, v126, v219, v176
	v_fma_f32 v221, v127, v220, v177
	s_waitcnt lgkmcnt(2)
	v_lshlrev_b32_e32 v206, 16, v206
	v_lshlrev_b32_e32 v207, 16, v207
	v_lshlrev_b32_e32 v208, 16, v208
	v_lshlrev_b32_e32 v209, 16, v209
	v_lshlrev_b32_e32 v210, 16, v210
	v_lshlrev_b32_e32 v211, 16, v211
	v_lshlrev_b32_e32 v212, 16, v212
	v_lshlrev_b32_e32 v213, 16, v213
	v_add_f32_e32 v214, v214, v206
	v_add_f32_e32 v215, v215, v207
	v_add_f32_e32 v216, v216, v208
	v_add_f32_e32 v217, v217, v209
	v_add_f32_e32 v218, v218, v210
	v_add_f32_e32 v219, v219, v211
	v_add_f32_e32 v220, v220, v212
	v_add_f32_e32 v221, v221, v213
	v_cvt_pk_bf16_f32 v206, v214, v215
	v_cvt_pk_bf16_f32 v208, v216, v217
	v_cvt_pk_bf16_f32 v210, v218, v219
	v_cvt_pk_bf16_f32 v212, v220, v221
	ds_write_b16 v197, v206 offset:0
	ds_write_b16_d16_hi v197, v206 offset:64
	ds_write_b16 v197, v208 offset:128
	ds_write_b16_d16_hi v197, v208 offset:192
	ds_write_b16 v197, v210 offset:256
	ds_write_b16_d16_hi v197, v210 offset:320
	ds_write_b16 v197, v212 offset:384
	ds_write_b16_d16_hi v197, v212 offset:448
	ds_read_b128 v[198:201], v130 offset:0
	ds_read_b128 v[214:217], v130 offset:576
	ds_read_b128 v[202:205], v131 offset:0
	ds_read_b128 v[218:221], v131 offset:576
	ds_read_b128 v[206:209], v130 offset:144
	ds_read_b128 v[222:225], v130 offset:720
	ds_read_b128 v[210:213], v131 offset:144
	s_waitcnt lgkmcnt(14)
	ds_read_b128 v[226:229], v131 offset:720
	s_waitcnt lgkmcnt(6)
	v_mfma_f32_16x16x32_bf16 v[100:103], v[198:201], v[20:23], v[12:15]
	v_mfma_f32_16x16x32_bf16 v[104:107], v[198:201], v[52:55], v[16:19]
	v_mfma_f32_16x16x32_bf16 v[108:111], v[198:201], v[84:87], v[242:245]
	v_mfma_f32_16x16x32_bf16 v[112:115], v[214:217], v[20:23], v[12:15]
	v_mfma_f32_16x16x32_bf16 v[138:141], v[214:217], v[52:55], v[16:19]
	v_mfma_f32_16x16x32_bf16 v[142:145], v[214:217], v[84:87], v[242:245]
	s_waitcnt lgkmcnt(4)
	v_mfma_f32_16x16x32_bf16 v[100:103], v[202:205], v[24:27], v[100:103]
	v_mfma_f32_16x16x32_bf16 v[104:107], v[202:205], v[56:59], v[104:107]
	v_mfma_f32_16x16x32_bf16 v[112:115], v[218:221], v[24:27], v[112:115]
	v_mfma_f32_16x16x32_bf16 v[138:141], v[218:221], v[56:59], v[138:141]
	ds_read_b128 v[198:201], v130 offset:288
	ds_read_b128 v[214:217], v130 offset:864
	ds_read_b128 v[202:205], v131 offset:288
	ds_read_b128 v[218:221], v131 offset:864
	s_waitcnt lgkmcnt(6)
	v_mfma_f32_16x16x32_bf16 v[100:103], v[206:209], v[28:31], v[100:103]
	v_mfma_f32_16x16x32_bf16 v[104:107], v[206:209], v[60:63], v[104:107]
	v_mfma_f32_16x16x32_bf16 v[108:111], v[206:209], v[88:91], v[108:111]
	v_mfma_f32_16x16x32_bf16 v[112:115], v[222:225], v[28:31], v[112:115]
	v_mfma_f32_16x16x32_bf16 v[138:141], v[222:225], v[60:63], v[138:141]
	v_mfma_f32_16x16x32_bf16 v[142:145], v[222:225], v[88:91], v[142:145]
	s_waitcnt lgkmcnt(4)
	v_mfma_f32_16x16x32_bf16 v[100:103], v[210:213], v[32:35], v[100:103]
	v_mfma_f32_16x16x32_bf16 v[104:107], v[210:213], v[64:67], v[104:107]
	v_mfma_f32_16x16x32_bf16 v[112:115], v[226:229], v[32:35], v[112:115]
	v_mfma_f32_16x16x32_bf16 v[138:141], v[226:229], v[64:67], v[138:141]
	ds_read_b128 v[206:209], v130 offset:432
	ds_read_b128 v[222:225], v130 offset:1008
	ds_read_b128 v[210:213], v131 offset:432
	ds_read_b128 v[226:229], v131 offset:1008
	s_waitcnt lgkmcnt(6)
	v_mfma_f32_16x16x32_bf16 v[100:103], v[198:201], v[36:39], v[100:103]
	v_mfma_f32_16x16x32_bf16 v[104:107], v[198:201], v[68:71], v[104:107]
	v_mfma_f32_16x16x32_bf16 v[108:111], v[198:201], v[92:95], v[108:111]
	v_mfma_f32_16x16x32_bf16 v[112:115], v[214:217], v[36:39], v[112:115]
	v_mfma_f32_16x16x32_bf16 v[138:141], v[214:217], v[68:71], v[138:141]
	v_mfma_f32_16x16x32_bf16 v[142:145], v[214:217], v[92:95], v[142:145]
	s_waitcnt lgkmcnt(4)
	v_mfma_f32_16x16x32_bf16 v[100:103], v[202:205], v[40:43], v[100:103]
	v_mfma_f32_16x16x32_bf16 v[104:107], v[202:205], v[72:75], v[104:107]
	v_mfma_f32_16x16x32_bf16 v[112:115], v[218:221], v[40:43], v[112:115]
	v_mfma_f32_16x16x32_bf16 v[138:141], v[218:221], v[72:75], v[138:141]
	s_waitcnt lgkmcnt(2)
	v_mfma_f32_16x16x32_bf16 v[100:103], v[206:209], v[44:47], v[100:103]
	v_mfma_f32_16x16x32_bf16 v[104:107], v[206:209], v[76:79], v[104:107]
	v_mfma_f32_16x16x32_bf16 v[108:111], v[206:209], v[96:99], v[108:111]
	v_mfma_f32_16x16x32_bf16 v[112:115], v[222:225], v[44:47], v[112:115]
	v_mfma_f32_16x16x32_bf16 v[138:141], v[222:225], v[76:79], v[138:141]
	v_mfma_f32_16x16x32_bf16 v[142:145], v[222:225], v[96:99], v[142:145]
	s_waitcnt lgkmcnt(0)
	v_mfma_f32_16x16x32_bf16 v[100:103], v[210:213], v[48:51], v[100:103]
	v_mfma_f32_16x16x32_bf16 v[104:107], v[210:213], v[80:83], v[104:107]
	v_mfma_f32_16x16x32_bf16 v[112:115], v[226:229], v[48:51], v[112:115]
	v_mfma_f32_16x16x32_bf16 v[138:141], v[226:229], v[80:83], v[138:141]
	s_waitcnt lgkmcnt(0)
	s_barrier
	s_waitcnt vmcnt(5)
	ds_write_b128 v134, v[230:233]
	ds_write_b128 v134, v[234:237] offset:4608
	ds_write_b128 v135, v[238:241]
	s_add_i32 s64, s4, 0
	s_mul_i32 s71, s64, 0x30000
	s_add_u32 s38, s60, s71
	s_addc_u32 s39, s61, 0
	s_lshl_b32 s64, s64, 12
	v_add_u32_e32 v136, s64, v195
	ds_read_b128 v[116:119], v136
	s_waitcnt vmcnt(3)
	s_waitcnt lgkmcnt(0)
	v_lshlrev_b32_e32 v136, 16, v116
	v_lshlrev_b32_e32 v137, 16, v8
	v_and_b32_e32 v168, 0xffff0000, v116
	v_and_b32_e32 v169, 0xffff0000, v8
	v_mul_f32_e32 v136, v136, v137
	v_mul_f32_e32 v168, v168, v169
	v_cvt_pk_bf16_f32 v116, v136, v168
	v_lshlrev_b32_e32 v136, 16, v117
	v_lshlrev_b32_e32 v137, 16, v9
	v_and_b32_e32 v168, 0xffff0000, v117
	v_and_b32_e32 v169, 0xffff0000, v9
	v_mul_f32_e32 v136, v136, v137
	v_mul_f32_e32 v168, v168, v169
	v_cvt_pk_bf16_f32 v117, v136, v168
	v_lshlrev_b32_e32 v136, 16, v118
	v_lshlrev_b32_e32 v137, 16, v10
	v_and_b32_e32 v168, 0xffff0000, v118
	v_and_b32_e32 v169, 0xffff0000, v10
	v_mul_f32_e32 v136, v136, v137
	v_mul_f32_e32 v168, v168, v169
	v_cvt_pk_bf16_f32 v118, v136, v168
	v_lshlrev_b32_e32 v136, 16, v119
	v_lshlrev_b32_e32 v137, 16, v11
	v_and_b32_e32 v168, 0xffff0000, v119
	v_and_b32_e32 v169, 0xffff0000, v11
	v_mul_f32_e32 v136, v136, v137
	v_mul_f32_e32 v168, v168, v169
	v_cvt_pk_bf16_f32 v119, v136, v168
	global_store_dwordx4 v255, v[116:119], s[38:39]
	s_add_i32 s64, s4, 1
	s_mul_i32 s71, s64, 0x30000
	s_add_u32 s38, s60, s71
	s_addc_u32 s39, s61, 0
	s_lshl_b32 s64, s64, 12
	global_load_dwordx4 v[8:11], v255, s[38:39]
	s_add_i32 s52, s4, 4
	s_min_u32 s52, s52, 31
	s_lshl_b32 s52, s52, 13
	s_add_u32 s26, s50, s52
	s_addc_u32 s27, s51, 0
	global_load_dwordx4 v[230:233], v154, s[26:27]
	global_load_dwordx4 v[234:237], v155, s[26:27]
	global_load_dwordx4 v[238:241], v159, s[26:27]
	v_exp_f32_e32 v198, v100
	v_exp_f32_e32 v199, v101
	v_exp_f32_e32 v200, v102
	v_exp_f32_e32 v201, v103
	v_exp_f32_e32 v202, v112
	v_exp_f32_e32 v203, v113
	v_exp_f32_e32 v204, v114
	v_exp_f32_e32 v205, v115
	v_exp_f32_e32 v214, v104
	v_add_f32_e32 v198, 1.0, v198
	v_exp_f32_e32 v215, v105
	v_add_f32_e32 v199, 1.0, v199
	v_exp_f32_e32 v216, v106
	v_add_f32_e32 v200, 1.0, v200
	v_exp_f32_e32 v217, v107
	v_add_f32_e32 v201, 1.0, v201
	v_exp_f32_e32 v218, v138
	v_add_f32_e32 v202, 1.0, v202
	v_exp_f32_e32 v219, v139
	v_add_f32_e32 v203, 1.0, v203
	v_exp_f32_e32 v220, v140
	v_add_f32_e32 v204, 1.0, v204
	v_exp_f32_e32 v221, v141
	v_add_f32_e32 v205, 1.0, v205
	v_rcp_f32_e32 v198, v198
	v_add_f32_e32 v214, 1.0, v214
	v_rcp_f32_e32 v199, v199
	v_add_f32_e32 v215, 1.0, v215
	v_rcp_f32_e32 v200, v200
	v_add_f32_e32 v216, 1.0, v216
	v_rcp_f32_e32 v201, v201
	v_add_f32_e32 v217, 1.0, v217
	v_rcp_f32_e32 v202, v202
	v_add_f32_e32 v218, 1.0, v218
	v_rcp_f32_e32 v203, v203
	v_add_f32_e32 v219, 1.0, v219
	v_rcp_f32_e32 v204, v204
	v_add_f32_e32 v220, 1.0, v220
	v_rcp_f32_e32 v205, v205
	v_add_f32_e32 v221, 1.0, v221
	v_mul_f32_e32 v198, v179, v198
	v_mul_f32_e32 v199, v179, v199
	v_mul_f32_e32 v200, v179, v200
	v_mul_f32_e32 v201, v179, v201
	v_mul_f32_e32 v202, v179, v202
	v_mul_f32_e32 v203, v179, v203
	v_mul_f32_e32 v204, v179, v204
	v_mul_f32_e32 v205, v179, v205
	v_exp_f32_e32 v120, v198
	v_exp_f32_e32 v121, v199
	v_exp_f32_e32 v122, v200
	v_exp_f32_e32 v123, v201
	v_exp_f32_e32 v124, v202
	v_exp_f32_e32 v125, v203
	v_exp_f32_e32 v126, v204
	v_exp_f32_e32 v127, v205
	v_fma_f32 v206, -v120, v120, 1.0
	v_fma_f32 v207, -v121, v121, 1.0
	v_fma_f32 v208, -v122, v122, 1.0
	v_fma_f32 v209, -v123, v123, 1.0
	v_fma_f32 v210, -v124, v124, 1.0
	v_fma_f32 v211, -v125, v125, 1.0
	v_fma_f32 v212, -v126, v126, 1.0
	v_fma_f32 v213, -v127, v127, 1.0
	v_max_f32_e32 v206, 0xda24260, v206
	v_max_f32_e32 v207, 0xda24260, v207
	v_max_f32_e32 v208, 0xda24260, v208
	v_max_f32_e32 v209, 0xda24260, v209
	v_max_f32_e32 v210, 0xda24260, v210
	v_max_f32_e32 v211, 0xda24260, v211
	v_max_f32_e32 v212, 0xda24260, v212
	v_max_f32_e32 v213, 0xda24260, v213
	v_mul_f32_e32 v198, v214, v206
	v_mul_f32_e32 v199, v215, v207
	v_mul_f32_e32 v200, v216, v208
	v_mul_f32_e32 v201, v217, v209
	v_mul_f32_e32 v202, v218, v210
	v_mul_f32_e32 v203, v219, v211
	v_mul_f32_e32 v204, v220, v212
	v_mul_f32_e32 v205, v221, v213
	v_mul_f32_e32 v214, v214, v198
	v_mul_f32_e32 v215, v215, v199
	v_mul_f32_e32 v216, v216, v200
	v_mul_f32_e32 v217, v217, v201
	v_mul_f32_e32 v218, v218, v202
	v_mul_f32_e32 v219, v219, v203
	v_mul_f32_e32 v220, v220, v204
	v_mul_f32_e32 v221, v221, v205
	v_rsq_f32_e32 v214, v214
	v_mul_f32_e32 v222, v108, v206
	v_rsq_f32_e32 v215, v215
	v_mul_f32_e32 v223, v109, v207
	v_rsq_f32_e32 v216, v216
	v_mul_f32_e32 v224, v110, v208
	v_rsq_f32_e32 v217, v217
	v_mul_f32_e32 v225, v111, v209
	v_rsq_f32_e32 v218, v218
	v_mul_f32_e32 v226, v142, v210
	v_rsq_f32_e32 v219, v219
	v_mul_f32_e32 v227, v143, v211
	v_rsq_f32_e32 v220, v220
	v_mul_f32_e32 v228, v144, v212
	v_rsq_f32_e32 v221, v221
	v_mul_f32_e32 v229, v145, v213
	v_mul_f32_e32 v170, v222, v214
	v_mul_f32_e32 v171, v223, v215
	v_mul_f32_e32 v172, v224, v216
	v_mul_f32_e32 v173, v225, v217
	v_mul_f32_e32 v174, v226, v218
	v_mul_f32_e32 v175, v227, v219
	v_mul_f32_e32 v176, v228, v220
	v_mul_f32_e32 v177, v229, v221
	s_add_i32 s52, s4, 1
	s_lshl_b32 s52, s52, 12
	v_add_u32_e32 v197, s52, v184
	ds_read_u16 v206, v197 offset:0
	ds_read_u16 v207, v197 offset:64
	ds_read_u16 v208, v197 offset:128
	ds_read_u16 v209, v197 offset:192
	ds_read_u16 v210, v197 offset:256
	ds_read_u16 v211, v197 offset:320
	ds_read_u16 v212, v197 offset:384
	ds_read_u16 v213, v197 offset:448
	v_mov_b32_e32 v198, v170
	v_mov_b32_e32 v199, v120
	v_fma_f32 v198, v121, v198, v171
	v_mul_f32_e32 v199, v199, v121
	v_fma_f32 v198, v122, v198, v172
	v_mul_f32_e32 v199, v199, v122
	v_fma_f32 v198, v123, v198, v173
	v_mul_f32_e32 v199, v199, v123
	v_fma_f32 v198, v124, v198, v174
	v_mul_f32_e32 v199, v199, v124
	v_fma_f32 v198, v125, v198, v175
	v_mul_f32_e32 v199, v199, v125
	v_fma_f32 v198, v126, v198, v176
	v_mul_f32_e32 v199, v199, v126
	v_fma_f32 v198, v127, v198, v177
	v_mul_f32_e32 v199, v199, v127
	v_mov_b32_e32 v164, v199
	v_mov_b32_e32 v166, v199
	v_mov_b32_e32 v246, v198
	v_mov_b32_e32 v248, v198
	s_nop 1
	v_permlane32_swap_b32 v164, v166
	v_permlane32_swap_b32 v246, v248
	s_nop 1
	v_mov_b32_e32 v165, v164
	v_mov_b32_e32 v167, v166
	v_mov_b32_e32 v247, v246
	v_mov_b32_e32 v249, v248
	s_nop 1
	v_permlane16_swap_b32 v164, v165
	v_permlane16_swap_b32 v166, v167
	v_permlane16_swap_b32 v246, v247
	v_permlane16_swap_b32 v248, v249
	s_nop 1
	v_mov_b32_e32 v251, v246
	v_mov_b32_e32 v250, v164
	v_fma_f32 v251, v251, v165, v247
	v_mul_f32_e32 v250, v250, v165
	v_fma_f32 v251, v251, v166, v248
	v_mul_f32_e32 v250, v250, v166
	v_fma_f32 v251, v251, v167, v249
	v_mul_f32_e32 v250, v250, v167
	s_mov_b64 exec, s[10:11]
	ds_write_b64 v182, v[250:251] offset:1024
	s_mov_b64 exec, -1
	s_waitcnt lgkmcnt(0)
	s_barrier
	ds_read2_b64 v[4:7], v183 offset0:128 offset1:144
	s_add_i32 s52, s4, 1
	s_lshl_b32 s52, s52, 12
	v_add_u32_e32 v197, s52, v184
	s_waitcnt lgkmcnt(0)
	v_fma_f32 v198, v180, v4, v5
	v_cndmask_b32_e64 v199, v180, v198, s[24:25]
	v_fma_f32 v180, v198, v6, v7
	v_fma_f32 v200, v199, v164, v246
	v_cndmask_b32_e64 v199, v199, v200, s[16:17]
	v_fma_f32 v200, v199, v165, v247
	v_cndmask_b32_e64 v199, v199, v200, s[20:21]
	v_fma_f32 v200, v199, v166, v248
	v_cndmask_b32_e64 v199, v199, v200, s[22:23]
	v_fma_f32 v214, v120, v199, v170
	v_fma_f32 v215, v121, v214, v171
	v_fma_f32 v216, v122, v215, v172
	v_fma_f32 v217, v123, v216, v173
	v_fma_f32 v218, v124, v217, v174
	v_fma_f32 v219, v125, v218, v175
	v_fma_f32 v220, v126, v219, v176
	v_fma_f32 v221, v127, v220, v177
	s_waitcnt lgkmcnt(2)
	v_lshlrev_b32_e32 v206, 16, v206
	v_lshlrev_b32_e32 v207, 16, v207
	v_lshlrev_b32_e32 v208, 16, v208
	v_lshlrev_b32_e32 v209, 16, v209
	v_lshlrev_b32_e32 v210, 16, v210
	v_lshlrev_b32_e32 v211, 16, v211
	v_lshlrev_b32_e32 v212, 16, v212
	v_lshlrev_b32_e32 v213, 16, v213
	v_add_f32_e32 v214, v214, v206
	v_add_f32_e32 v215, v215, v207
	v_add_f32_e32 v216, v216, v208
	v_add_f32_e32 v217, v217, v209
	v_add_f32_e32 v218, v218, v210
	v_add_f32_e32 v219, v219, v211
	v_add_f32_e32 v220, v220, v212
	v_add_f32_e32 v221, v221, v213
	v_cvt_pk_bf16_f32 v206, v214, v215
	v_cvt_pk_bf16_f32 v208, v216, v217
	v_cvt_pk_bf16_f32 v210, v218, v219
	v_cvt_pk_bf16_f32 v212, v220, v221
	ds_write_b16 v197, v206 offset:0
	ds_write_b16_d16_hi v197, v206 offset:64
	ds_write_b16 v197, v208 offset:128
	ds_write_b16_d16_hi v197, v208 offset:192
	ds_write_b16 v197, v210 offset:256
	ds_write_b16_d16_hi v197, v210 offset:320
	ds_write_b16 v197, v212 offset:384
	ds_write_b16_d16_hi v197, v212 offset:448
	s_add_i32 s4, s4, 2
	s_cmp_lt_u32 s4, 32
	s_cbranch_scc1 .Lrec2_loopB_d0
	s_waitcnt lgkmcnt(0)
	s_barrier
	s_add_i32 s64, s4, -1
	s_mul_i32 s71, s64, 0x30000
	s_add_u32 s38, s60, s71
	s_addc_u32 s39, s61, 0
	s_lshl_b32 s64, s64, 12
	v_add_u32_e32 v136, s64, v195
	ds_read_b128 v[116:119], v136
	s_waitcnt vmcnt(3)
	s_waitcnt lgkmcnt(0)
	v_lshlrev_b32_e32 v136, 16, v116
	v_lshlrev_b32_e32 v137, 16, v8
	v_and_b32_e32 v168, 0xffff0000, v116
	v_and_b32_e32 v169, 0xffff0000, v8
	v_mul_f32_e32 v136, v136, v137
	v_mul_f32_e32 v168, v168, v169
	v_cvt_pk_bf16_f32 v116, v136, v168
	v_lshlrev_b32_e32 v136, 16, v117
	v_lshlrev_b32_e32 v137, 16, v9
	v_and_b32_e32 v168, 0xffff0000, v117
	v_and_b32_e32 v169, 0xffff0000, v9
	v_mul_f32_e32 v136, v136, v137
	v_mul_f32_e32 v168, v168, v169
	v_cvt_pk_bf16_f32 v117, v136, v168
	v_lshlrev_b32_e32 v136, 16, v118
	v_lshlrev_b32_e32 v137, 16, v10
	v_and_b32_e32 v168, 0xffff0000, v118
	v_and_b32_e32 v169, 0xffff0000, v10
	v_mul_f32_e32 v136, v136, v137
	v_mul_f32_e32 v168, v168, v169
	v_cvt_pk_bf16_f32 v118, v136, v168
	v_lshlrev_b32_e32 v136, 16, v119
	v_lshlrev_b32_e32 v137, 16, v11
	v_and_b32_e32 v168, 0xffff0000, v119
	v_and_b32_e32 v169, 0xffff0000, v11
	v_mul_f32_e32 v136, v136, v137
	v_mul_f32_e32 v168, v168, v169
	v_cvt_pk_bf16_f32 v119, v136, v168
	global_store_dwordx4 v255, v[116:119], s[38:39]
	s_barrier
	s_branch .Lrec2_done

.Lrec2_loopB_d1:
	ds_read_b128 v[198:201], v130 offset:0
	ds_read_b128 v[214:217], v130 offset:576
	ds_read_b128 v[202:205], v131 offset:0
	ds_read_b128 v[218:221], v131 offset:576
	ds_read_b128 v[206:209], v130 offset:144
	ds_read_b128 v[222:225], v130 offset:720
	ds_read_b128 v[210:213], v131 offset:144
	s_waitcnt lgkmcnt(14)
	ds_read_b128 v[226:229], v131 offset:720
	s_waitcnt lgkmcnt(6)
	v_mfma_f32_16x16x32_bf16 v[100:103], v[198:201], v[20:23], v[12:15]
	v_mfma_f32_16x16x32_bf16 v[104:107], v[198:201], v[52:55], v[16:19]
	v_mfma_f32_16x16x32_bf16 v[108:111], v[198:201], v[84:87], v[242:245]
	v_mfma_f32_16x16x32_bf16 v[112:115], v[214:217], v[20:23], v[12:15]
	v_mfma_f32_16x16x32_bf16 v[138:141], v[214:217], v[52:55], v[16:19]
	v_mfma_f32_16x16x32_bf16 v[142:145], v[214:217], v[84:87], v[242:245]
	s_waitcnt lgkmcnt(4)
	v_mfma_f32_16x16x32_bf16 v[100:103], v[202:205], v[24:27], v[100:103]
	v_mfma_f32_16x16x32_bf16 v[104:107], v[202:205], v[56:59], v[104:107]
	v_mfma_f32_16x16x32_bf16 v[112:115], v[218:221], v[24:27], v[112:115]
	v_mfma_f32_16x16x32_bf16 v[138:141], v[218:221], v[56:59], v[138:141]
	ds_read_b128 v[198:201], v130 offset:288
	ds_read_b128 v[214:217], v130 offset:864
	ds_read_b128 v[202:205], v131 offset:288
	ds_read_b128 v[218:221], v131 offset:864
	s_waitcnt lgkmcnt(6)
	v_mfma_f32_16x16x32_bf16 v[100:103], v[206:209], v[28:31], v[100:103]
	v_mfma_f32_16x16x32_bf16 v[104:107], v[206:209], v[60:63], v[104:107]
	v_mfma_f32_16x16x32_bf16 v[108:111], v[206:209], v[88:91], v[108:111]
	v_mfma_f32_16x16x32_bf16 v[112:115], v[222:225], v[28:31], v[112:115]
	v_mfma_f32_16x16x32_bf16 v[138:141], v[222:225], v[60:63], v[138:141]
	v_mfma_f32_16x16x32_bf16 v[142:145], v[222:225], v[88:91], v[142:145]
	s_waitcnt lgkmcnt(4)
	v_mfma_f32_16x16x32_bf16 v[100:103], v[210:213], v[32:35], v[100:103]
	v_mfma_f32_16x16x32_bf16 v[104:107], v[210:213], v[64:67], v[104:107]
	v_mfma_f32_16x16x32_bf16 v[112:115], v[226:229], v[32:35], v[112:115]
	v_mfma_f32_16x16x32_bf16 v[138:141], v[226:229], v[64:67], v[138:141]
	ds_read_b128 v[206:209], v130 offset:432
	ds_read_b128 v[222:225], v130 offset:1008
	ds_read_b128 v[210:213], v131 offset:432
	ds_read_b128 v[226:229], v131 offset:1008
	s_waitcnt lgkmcnt(6)
	v_mfma_f32_16x16x32_bf16 v[100:103], v[198:201], v[36:39], v[100:103]
	v_mfma_f32_16x16x32_bf16 v[104:107], v[198:201], v[68:71], v[104:107]
	v_mfma_f32_16x16x32_bf16 v[108:111], v[198:201], v[92:95], v[108:111]
	v_mfma_f32_16x16x32_bf16 v[112:115], v[214:217], v[36:39], v[112:115]
	v_mfma_f32_16x16x32_bf16 v[138:141], v[214:217], v[68:71], v[138:141]
	v_mfma_f32_16x16x32_bf16 v[142:145], v[214:217], v[92:95], v[142:145]
	s_waitcnt lgkmcnt(4)
	v_mfma_f32_16x16x32_bf16 v[100:103], v[202:205], v[40:43], v[100:103]
	v_mfma_f32_16x16x32_bf16 v[104:107], v[202:205], v[72:75], v[104:107]
	v_mfma_f32_16x16x32_bf16 v[112:115], v[218:221], v[40:43], v[112:115]
	v_mfma_f32_16x16x32_bf16 v[138:141], v[218:221], v[72:75], v[138:141]
	s_waitcnt lgkmcnt(2)
	v_mfma_f32_16x16x32_bf16 v[100:103], v[206:209], v[44:47], v[100:103]
	v_mfma_f32_16x16x32_bf16 v[104:107], v[206:209], v[76:79], v[104:107]
	v_mfma_f32_16x16x32_bf16 v[108:111], v[206:209], v[96:99], v[108:111]
	v_mfma_f32_16x16x32_bf16 v[112:115], v[222:225], v[44:47], v[112:115]
	v_mfma_f32_16x16x32_bf16 v[138:141], v[222:225], v[76:79], v[138:141]
	v_mfma_f32_16x16x32_bf16 v[142:145], v[222:225], v[96:99], v[142:145]
	s_waitcnt lgkmcnt(0)
	v_mfma_f32_16x16x32_bf16 v[100:103], v[210:213], v[48:51], v[100:103]
	v_mfma_f32_16x16x32_bf16 v[104:107], v[210:213], v[80:83], v[104:107]
	v_mfma_f32_16x16x32_bf16 v[112:115], v[226:229], v[48:51], v[112:115]
	v_mfma_f32_16x16x32_bf16 v[138:141], v[226:229], v[80:83], v[138:141]
	s_waitcnt lgkmcnt(0)
	s_barrier
	s_waitcnt vmcnt(5)
	ds_write_b128 v134, v[146:149]
	ds_write_b128 v134, v[150:153] offset:4608
	ds_write_b128 v135, v[160:163]
	s_add_i32 s64, s4, -1
	s_sub_i32 s64, 31, s64
	s_mul_i32 s71, s64, 0x30000
	s_add_u32 s38, s60, s71
	s_addc_u32 s39, s61, 0
	s_lshl_b32 s64, s64, 12
	v_add_u32_e32 v136, s64, v195
	ds_read_b128 v[116:119], v136
	s_waitcnt vmcnt(3)
	s_waitcnt lgkmcnt(0)
	v_lshlrev_b32_e32 v136, 16, v116
	v_lshlrev_b32_e32 v137, 16, v8
	v_and_b32_e32 v168, 0xffff0000, v116
	v_and_b32_e32 v169, 0xffff0000, v8
	v_mul_f32_e32 v136, v136, v137
	v_mul_f32_e32 v168, v168, v169
	v_cvt_pk_bf16_f32 v116, v136, v168
	v_lshlrev_b32_e32 v136, 16, v117
	v_lshlrev_b32_e32 v137, 16, v9
	v_and_b32_e32 v168, 0xffff0000, v117
	v_and_b32_e32 v169, 0xffff0000, v9
	v_mul_f32_e32 v136, v136, v137
	v_mul_f32_e32 v168, v168, v169
	v_cvt_pk_bf16_f32 v117, v136, v168
	v_lshlrev_b32_e32 v136, 16, v118
	v_lshlrev_b32_e32 v137, 16, v10
	v_and_b32_e32 v168, 0xffff0000, v118
	v_and_b32_e32 v169, 0xffff0000, v10
	v_mul_f32_e32 v136, v136, v137
	v_mul_f32_e32 v168, v168, v169
	v_cvt_pk_bf16_f32 v118, v136, v168
	v_lshlrev_b32_e32 v136, 16, v119
	v_lshlrev_b32_e32 v137, 16, v11
	v_and_b32_e32 v168, 0xffff0000, v119
	v_and_b32_e32 v169, 0xffff0000, v11
	v_mul_f32_e32 v136, v136, v137
	v_mul_f32_e32 v168, v168, v169
	v_cvt_pk_bf16_f32 v119, v136, v168
	global_store_dwordx4 v255, v[116:119], s[38:39]
	s_add_i32 s64, s4, 0
	s_sub_i32 s64, 31, s64
	s_mul_i32 s71, s64, 0x30000
	s_add_u32 s38, s60, s71
	s_addc_u32 s39, s61, 0
	s_lshl_b32 s64, s64, 12
	global_load_dwordx4 v[8:11], v255, s[38:39]
	s_add_i32 s52, s4, 3
	s_min_u32 s52, s52, 31
	s_sub_i32 s52, 31, s52
	s_lshl_b32 s52, s52, 13
	s_add_u32 s26, s50, s52
	s_addc_u32 s27, s51, 0
	global_load_dwordx4 v[146:149], v154, s[26:27]
	global_load_dwordx4 v[150:153], v155, s[26:27]
	global_load_dwordx4 v[160:163], v159, s[26:27]
	v_exp_f32_e32 v198, v100
	v_exp_f32_e32 v199, v101
	v_exp_f32_e32 v200, v102
	v_exp_f32_e32 v201, v103
	v_exp_f32_e32 v202, v112
	v_exp_f32_e32 v203, v113
	v_exp_f32_e32 v204, v114
	v_exp_f32_e32 v205, v115
	v_exp_f32_e32 v214, v104
	v_add_f32_e32 v198, 1.0, v198
	v_exp_f32_e32 v215, v105
	v_add_f32_e32 v199, 1.0, v199
	v_exp_f32_e32 v216, v106
	v_add_f32_e32 v200, 1.0, v200
	v_exp_f32_e32 v217, v107
	v_add_f32_e32 v201, 1.0, v201
	v_exp_f32_e32 v218, v138
	v_add_f32_e32 v202, 1.0, v202
	v_exp_f32_e32 v219, v139
	v_add_f32_e32 v203, 1.0, v203
	v_exp_f32_e32 v220, v140
	v_add_f32_e32 v204, 1.0, v204
	v_exp_f32_e32 v221, v141
	v_add_f32_e32 v205, 1.0, v205
	v_rcp_f32_e32 v198, v198
	v_add_f32_e32 v214, 1.0, v214
	v_rcp_f32_e32 v199, v199
	v_add_f32_e32 v215, 1.0, v215
	v_rcp_f32_e32 v200, v200
	v_add_f32_e32 v216, 1.0, v216
	v_rcp_f32_e32 v201, v201
	v_add_f32_e32 v217, 1.0, v217
	v_rcp_f32_e32 v202, v202
	v_add_f32_e32 v218, 1.0, v218
	v_rcp_f32_e32 v203, v203
	v_add_f32_e32 v219, 1.0, v219
	v_rcp_f32_e32 v204, v204
	v_add_f32_e32 v220, 1.0, v220
	v_rcp_f32_e32 v205, v205
	v_add_f32_e32 v221, 1.0, v221
	v_mul_f32_e32 v198, v179, v198
	v_mul_f32_e32 v199, v179, v199
	v_mul_f32_e32 v200, v179, v200
	v_mul_f32_e32 v201, v179, v201
	v_mul_f32_e32 v202, v179, v202
	v_mul_f32_e32 v203, v179, v203
	v_mul_f32_e32 v204, v179, v204
	v_mul_f32_e32 v205, v179, v205
	v_exp_f32_e32 v120, v198
	v_exp_f32_e32 v121, v199
	v_exp_f32_e32 v122, v200
	v_exp_f32_e32 v123, v201
	v_exp_f32_e32 v124, v202
	v_exp_f32_e32 v125, v203
	v_exp_f32_e32 v126, v204
	v_exp_f32_e32 v127, v205
	v_fma_f32 v206, -v120, v120, 1.0
	v_fma_f32 v207, -v121, v121, 1.0
	v_fma_f32 v208, -v122, v122, 1.0
	v_fma_f32 v209, -v123, v123, 1.0
	v_fma_f32 v210, -v124, v124, 1.0
	v_fma_f32 v211, -v125, v125, 1.0
	v_fma_f32 v212, -v126, v126, 1.0
	v_fma_f32 v213, -v127, v127, 1.0
	v_max_f32_e32 v206, 0xda24260, v206
	v_max_f32_e32 v207, 0xda24260, v207
	v_max_f32_e32 v208, 0xda24260, v208
	v_max_f32_e32 v209, 0xda24260, v209
	v_max_f32_e32 v210, 0xda24260, v210
	v_max_f32_e32 v211, 0xda24260, v211
	v_max_f32_e32 v212, 0xda24260, v212
	v_max_f32_e32 v213, 0xda24260, v213
	v_mul_f32_e32 v198, v214, v206
	v_mul_f32_e32 v199, v215, v207
	v_mul_f32_e32 v200, v216, v208
	v_mul_f32_e32 v201, v217, v209
	v_mul_f32_e32 v202, v218, v210
	v_mul_f32_e32 v203, v219, v211
	v_mul_f32_e32 v204, v220, v212
	v_mul_f32_e32 v205, v221, v213
	v_mul_f32_e32 v214, v214, v198
	v_mul_f32_e32 v215, v215, v199
	v_mul_f32_e32 v216, v216, v200
	v_mul_f32_e32 v217, v217, v201
	v_mul_f32_e32 v218, v218, v202
	v_mul_f32_e32 v219, v219, v203
	v_mul_f32_e32 v220, v220, v204
	v_mul_f32_e32 v221, v221, v205
	v_rsq_f32_e32 v214, v214
	v_mul_f32_e32 v222, v108, v206
	v_rsq_f32_e32 v215, v215
	v_mul_f32_e32 v223, v109, v207
	v_rsq_f32_e32 v216, v216
	v_mul_f32_e32 v224, v110, v208
	v_rsq_f32_e32 v217, v217
	v_mul_f32_e32 v225, v111, v209
	v_rsq_f32_e32 v218, v218
	v_mul_f32_e32 v226, v142, v210
	v_rsq_f32_e32 v219, v219
	v_mul_f32_e32 v227, v143, v211
	v_rsq_f32_e32 v220, v220
	v_mul_f32_e32 v228, v144, v212
	v_rsq_f32_e32 v221, v221
	v_mul_f32_e32 v229, v145, v213
	v_mul_f32_e32 v170, v222, v214
	v_mul_f32_e32 v171, v223, v215
	v_mul_f32_e32 v172, v224, v216
	v_mul_f32_e32 v173, v225, v217
	v_mul_f32_e32 v174, v226, v218
	v_mul_f32_e32 v175, v227, v219
	v_mul_f32_e32 v176, v228, v220
	v_mul_f32_e32 v177, v229, v221
	s_add_i32 s52, s4, 0
	s_sub_i32 s52, 31, s52
	s_lshl_b32 s52, s52, 12
	v_add_u32_e32 v197, s52, v184
	ds_read_u16 v206, v197 offset:0
	ds_read_u16 v207, v197 offset:64
	ds_read_u16 v208, v197 offset:128
	ds_read_u16 v209, v197 offset:192
	ds_read_u16 v210, v197 offset:256
	ds_read_u16 v211, v197 offset:320
	ds_read_u16 v212, v197 offset:384
	ds_read_u16 v213, v197 offset:448
	v_mov_b32_e32 v198, v177
	v_mov_b32_e32 v199, v127
	v_fma_f32 v198, v126, v198, v176
	v_mul_f32_e32 v199, v199, v126
	v_fma_f32 v198, v125, v198, v175
	v_mul_f32_e32 v199, v199, v125
	v_fma_f32 v198, v124, v198, v174
	v_mul_f32_e32 v199, v199, v124
	v_fma_f32 v198, v123, v198, v173
	v_mul_f32_e32 v199, v199, v123
	v_fma_f32 v198, v122, v198, v172
	v_mul_f32_e32 v199, v199, v122
	v_fma_f32 v198, v121, v198, v171
	v_mul_f32_e32 v199, v199, v121
	v_fma_f32 v198, v120, v198, v170
	v_mul_f32_e32 v199, v199, v120
	v_mov_b32_e32 v164, v199
	v_mov_b32_e32 v166, v199
	v_mov_b32_e32 v246, v198
	v_mov_b32_e32 v248, v198
	s_nop 1
	v_permlane32_swap_b32 v164, v166
	v_permlane32_swap_b32 v246, v248
	s_nop 1
	v_mov_b32_e32 v165, v164
	v_mov_b32_e32 v167, v166
	v_mov_b32_e32 v247, v246
	v_mov_b32_e32 v249, v248
	s_nop 1
	v_permlane16_swap_b32 v164, v165
	v_permlane16_swap_b32 v166, v167
	v_permlane16_swap_b32 v246, v247
	v_permlane16_swap_b32 v248, v249
	s_nop 1
	v_mov_b32_e32 v251, v249
	v_mov_b32_e32 v250, v167
	v_fma_f32 v251, v251, v166, v248
	v_mul_f32_e32 v250, v250, v166
	v_fma_f32 v251, v251, v165, v247
	v_mul_f32_e32 v250, v250, v165
	v_fma_f32 v251, v251, v164, v246
	v_mul_f32_e32 v250, v250, v164
	s_mov_b64 exec, s[10:11]
	ds_write_b64 v182, v[250:251] offset:0
	s_mov_b64 exec, -1
	s_waitcnt lgkmcnt(0)
	s_barrier
	ds_read2_b64 v[4:7], v183 offset0:0 offset1:16
	s_add_i32 s52, s4, 0
	s_sub_i32 s52, 31, s52
	s_lshl_b32 s52, s52, 12
	v_add_u32_e32 v197, s52, v184
	s_waitcnt lgkmcnt(0)
	v_fma_f32 v198, v180, v6, v7
	v_cndmask_b32_e64 v199, v180, v198, s[24:25]
	v_fma_f32 v180, v198, v4, v5
	v_fma_f32 v200, v199, v167, v249
	v_cndmask_b32_e64 v199, v199, v200, s[16:17]
	v_fma_f32 v200, v199, v166, v248
	v_cndmask_b32_e64 v199, v199, v200, s[20:21]
	v_fma_f32 v200, v199, v165, v247
	v_cndmask_b32_e64 v199, v199, v200, s[22:23]
	v_fma_f32 v221, v127, v199, v177
	v_fma_f32 v220, v126, v221, v176
	v_fma_f32 v219, v125, v220, v175
	v_fma_f32 v218, v124, v219, v174
	v_fma_f32 v217, v123, v218, v173
	v_fma_f32 v216, v122, v217, v172
	v_fma_f32 v215, v121, v216, v171
	v_fma_f32 v214, v120, v215, v170
	s_waitcnt lgkmcnt(2)
	v_lshlrev_b32_e32 v206, 16, v206
	v_lshlrev_b32_e32 v207, 16, v207
	v_lshlrev_b32_e32 v208, 16, v208
	v_lshlrev_b32_e32 v209, 16, v209
	v_lshlrev_b32_e32 v210, 16, v210
	v_lshlrev_b32_e32 v211, 16, v211
	v_lshlrev_b32_e32 v212, 16, v212
	v_lshlrev_b32_e32 v213, 16, v213
	v_add_f32_e32 v214, v214, v206
	v_add_f32_e32 v215, v215, v207
	v_add_f32_e32 v216, v216, v208
	v_add_f32_e32 v217, v217, v209
	v_add_f32_e32 v218, v218, v210
	v_add_f32_e32 v219, v219, v211
	v_add_f32_e32 v220, v220, v212
	v_add_f32_e32 v221, v221, v213
	v_cvt_pk_bf16_f32 v206, v214, v215
	v_cvt_pk_bf16_f32 v208, v216, v217
	v_cvt_pk_bf16_f32 v210, v218, v219
	v_cvt_pk_bf16_f32 v212, v220, v221
	ds_write_b16 v197, v206 offset:0
	ds_write_b16_d16_hi v197, v206 offset:64
	ds_write_b16 v197, v208 offset:128
	ds_write_b16_d16_hi v197, v208 offset:192
	ds_write_b16 v197, v210 offset:256
	ds_write_b16_d16_hi v197, v210 offset:320
	ds_write_b16 v197, v212 offset:384
	ds_write_b16_d16_hi v197, v212 offset:448
	ds_read_b128 v[198:201], v130 offset:0
	ds_read_b128 v[214:217], v130 offset:576
	ds_read_b128 v[202:205], v131 offset:0
	ds_read_b128 v[218:221], v131 offset:576
	ds_read_b128 v[206:209], v130 offset:144
	ds_read_b128 v[222:225], v130 offset:720
	ds_read_b128 v[210:213], v131 offset:144
	s_waitcnt lgkmcnt(14)
	ds_read_b128 v[226:229], v131 offset:720
	s_waitcnt lgkmcnt(6)
	v_mfma_f32_16x16x32_bf16 v[100:103], v[198:201], v[20:23], v[12:15]
	v_mfma_f32_16x16x32_bf16 v[104:107], v[198:201], v[52:55], v[16:19]
	v_mfma_f32_16x16x32_bf16 v[108:111], v[198:201], v[84:87], v[242:245]
	v_mfma_f32_16x16x32_bf16 v[112:115], v[214:217], v[20:23], v[12:15]
	v_mfma_f32_16x16x32_bf16 v[138:141], v[214:217], v[52:55], v[16:19]
	v_mfma_f32_16x16x32_bf16 v[142:145], v[214:217], v[84:87], v[242:245]
	s_waitcnt lgkmcnt(4)
	v_mfma_f32_16x16x32_bf16 v[100:103], v[202:205], v[24:27], v[100:103]
	v_mfma_f32_16x16x32_bf16 v[104:107], v[202:205], v[56:59], v[104:107]
	v_mfma_f32_16x16x32_bf16 v[112:115], v[218:221], v[24:27], v[112:115]
	v_mfma_f32_16x16x32_bf16 v[138:141], v[218:221], v[56:59], v[138:141]
	ds_read_b128 v[198:201], v130 offset:288
	ds_read_b128 v[214:217], v130 offset:864
	ds_read_b128 v[202:205], v131 offset:288
	ds_read_b128 v[218:221], v131 offset:864
	s_waitcnt lgkmcnt(6)
	v_mfma_f32_16x16x32_bf16 v[100:103], v[206:209], v[28:31], v[100:103]
	v_mfma_f32_16x16x32_bf16 v[104:107], v[206:209], v[60:63], v[104:107]
	v_mfma_f32_16x16x32_bf16 v[108:111], v[206:209], v[88:91], v[108:111]
	v_mfma_f32_16x16x32_bf16 v[112:115], v[222:225], v[28:31], v[112:115]
	v_mfma_f32_16x16x32_bf16 v[138:141], v[222:225], v[60:63], v[138:141]
	v_mfma_f32_16x16x32_bf16 v[142:145], v[222:225], v[88:91], v[142:145]
	s_waitcnt lgkmcnt(4)
	v_mfma_f32_16x16x32_bf16 v[100:103], v[210:213], v[32:35], v[100:103]
	v_mfma_f32_16x16x32_bf16 v[104:107], v[210:213], v[64:67], v[104:107]
	v_mfma_f32_16x16x32_bf16 v[112:115], v[226:229], v[32:35], v[112:115]
	v_mfma_f32_16x16x32_bf16 v[138:141], v[226:229], v[64:67], v[138:141]
	ds_read_b128 v[206:209], v130 offset:432
	ds_read_b128 v[222:225], v130 offset:1008
	ds_read_b128 v[210:213], v131 offset:432
	ds_read_b128 v[226:229], v131 offset:1008
	s_waitcnt lgkmcnt(6)
	v_mfma_f32_16x16x32_bf16 v[100:103], v[198:201], v[36:39], v[100:103]
	v_mfma_f32_16x16x32_bf16 v[104:107], v[198:201], v[68:71], v[104:107]
	v_mfma_f32_16x16x32_bf16 v[108:111], v[198:201], v[92:95], v[108:111]
	v_mfma_f32_16x16x32_bf16 v[112:115], v[214:217], v[36:39], v[112:115]
	v_mfma_f32_16x16x32_bf16 v[138:141], v[214:217], v[68:71], v[138:141]
	v_mfma_f32_16x16x32_bf16 v[142:145], v[214:217], v[92:95], v[142:145]
	s_waitcnt lgkmcnt(4)
	v_mfma_f32_16x16x32_bf16 v[100:103], v[202:205], v[40:43], v[100:103]
	v_mfma_f32_16x16x32_bf16 v[104:107], v[202:205], v[72:75], v[104:107]
	v_mfma_f32_16x16x32_bf16 v[112:115], v[218:221], v[40:43], v[112:115]
	v_mfma_f32_16x16x32_bf16 v[138:141], v[218:221], v[72:75], v[138:141]
	s_waitcnt lgkmcnt(2)
	v_mfma_f32_16x16x32_bf16 v[100:103], v[206:209], v[44:47], v[100:103]
	v_mfma_f32_16x16x32_bf16 v[104:107], v[206:209], v[76:79], v[104:107]
	v_mfma_f32_16x16x32_bf16 v[108:111], v[206:209], v[96:99], v[108:111]
	v_mfma_f32_16x16x32_bf16 v[112:115], v[222:225], v[44:47], v[112:115]
	v_mfma_f32_16x16x32_bf16 v[138:141], v[222:225], v[76:79], v[138:141]
	v_mfma_f32_16x16x32_bf16 v[142:145], v[222:225], v[96:99], v[142:145]
	s_waitcnt lgkmcnt(0)
	v_mfma_f32_16x16x32_bf16 v[100:103], v[210:213], v[48:51], v[100:103]
	v_mfma_f32_16x16x32_bf16 v[104:107], v[210:213], v[80:83], v[104:107]
	v_mfma_f32_16x16x32_bf16 v[112:115], v[226:229], v[48:51], v[112:115]
	v_mfma_f32_16x16x32_bf16 v[138:141], v[226:229], v[80:83], v[138:141]
	s_waitcnt lgkmcnt(0)
	s_barrier
	s_waitcnt vmcnt(5)
	ds_write_b128 v134, v[230:233]
	ds_write_b128 v134, v[234:237] offset:4608
	ds_write_b128 v135, v[238:241]
	s_add_i32 s64, s4, 0
	s_sub_i32 s64, 31, s64
	s_mul_i32 s71, s64, 0x30000
	s_add_u32 s38, s60, s71
	s_addc_u32 s39, s61, 0
	s_lshl_b32 s64, s64, 12
	v_add_u32_e32 v136, s64, v195
	ds_read_b128 v[116:119], v136
	s_waitcnt vmcnt(3)
	s_waitcnt lgkmcnt(0)
	v_lshlrev_b32_e32 v136, 16, v116
	v_lshlrev_b32_e32 v137, 16, v8
	v_and_b32_e32 v168, 0xffff0000, v116
	v_and_b32_e32 v169, 0xffff0000, v8
	v_mul_f32_e32 v136, v136, v137
	v_mul_f32_e32 v168, v168, v169
	v_cvt_pk_bf16_f32 v116, v136, v168
	v_lshlrev_b32_e32 v136, 16, v117
	v_lshlrev_b32_e32 v137, 16, v9
	v_and_b32_e32 v168, 0xffff0000, v117
	v_and_b32_e32 v169, 0xffff0000, v9
	v_mul_f32_e32 v136, v136, v137
	v_mul_f32_e32 v168, v168, v169
	v_cvt_pk_bf16_f32 v117, v136, v168
	v_lshlrev_b32_e32 v136, 16, v118
	v_lshlrev_b32_e32 v137, 16, v10
	v_and_b32_e32 v168, 0xffff0000, v118
	v_and_b32_e32 v169, 0xffff0000, v10
	v_mul_f32_e32 v136, v136, v137
	v_mul_f32_e32 v168, v168, v169
	v_cvt_pk_bf16_f32 v118, v136, v168
	v_lshlrev_b32_e32 v136, 16, v119
	v_lshlrev_b32_e32 v137, 16, v11
	v_and_b32_e32 v168, 0xffff0000, v119
	v_and_b32_e32 v169, 0xffff0000, v11
	v_mul_f32_e32 v136, v136, v137
	v_mul_f32_e32 v168, v168, v169
	v_cvt_pk_bf16_f32 v119, v136, v168
	global_store_dwordx4 v255, v[116:119], s[38:39]
	s_add_i32 s64, s4, 1
	s_sub_i32 s64, 31, s64
	s_mul_i32 s71, s64, 0x30000
	s_add_u32 s38, s60, s71
	s_addc_u32 s39, s61, 0
	s_lshl_b32 s64, s64, 12
	global_load_dwordx4 v[8:11], v255, s[38:39]
	s_add_i32 s52, s4, 4
	s_min_u32 s52, s52, 31
	s_sub_i32 s52, 31, s52
	s_lshl_b32 s52, s52, 13
	s_add_u32 s26, s50, s52
	s_addc_u32 s27, s51, 0
	global_load_dwordx4 v[230:233], v154, s[26:27]
	global_load_dwordx4 v[234:237], v155, s[26:27]
	global_load_dwordx4 v[238:241], v159, s[26:27]
	v_exp_f32_e32 v198, v100
	v_exp_f32_e32 v199, v101
	v_exp_f32_e32 v200, v102
	v_exp_f32_e32 v201, v103
	v_exp_f32_e32 v202, v112
	v_exp_f32_e32 v203, v113
	v_exp_f32_e32 v204, v114
	v_exp_f32_e32 v205, v115
	v_exp_f32_e32 v214, v104
	v_add_f32_e32 v198, 1.0, v198
	v_exp_f32_e32 v215, v105
	v_add_f32_e32 v199, 1.0, v199
	v_exp_f32_e32 v216, v106
	v_add_f32_e32 v200, 1.0, v200
	v_exp_f32_e32 v217, v107
	v_add_f32_e32 v201, 1.0, v201
	v_exp_f32_e32 v218, v138
	v_add_f32_e32 v202, 1.0, v202
	v_exp_f32_e32 v219, v139
	v_add_f32_e32 v203, 1.0, v203
	v_exp_f32_e32 v220, v140
	v_add_f32_e32 v204, 1.0, v204
	v_exp_f32_e32 v221, v141
	v_add_f32_e32 v205, 1.0, v205
	v_rcp_f32_e32 v198, v198
	v_add_f32_e32 v214, 1.0, v214
	v_rcp_f32_e32 v199, v199
	v_add_f32_e32 v215, 1.0, v215
	v_rcp_f32_e32 v200, v200
	v_add_f32_e32 v216, 1.0, v216
	v_rcp_f32_e32 v201, v201
	v_add_f32_e32 v217, 1.0, v217
	v_rcp_f32_e32 v202, v202
	v_add_f32_e32 v218, 1.0, v218
	v_rcp_f32_e32 v203, v203
	v_add_f32_e32 v219, 1.0, v219
	v_rcp_f32_e32 v204, v204
	v_add_f32_e32 v220, 1.0, v220
	v_rcp_f32_e32 v205, v205
	v_add_f32_e32 v221, 1.0, v221
	v_mul_f32_e32 v198, v179, v198
	v_mul_f32_e32 v199, v179, v199
	v_mul_f32_e32 v200, v179, v200
	v_mul_f32_e32 v201, v179, v201
	v_mul_f32_e32 v202, v179, v202
	v_mul_f32_e32 v203, v179, v203
	v_mul_f32_e32 v204, v179, v204
	v_mul_f32_e32 v205, v179, v205
	v_exp_f32_e32 v120, v198
	v_exp_f32_e32 v121, v199
	v_exp_f32_e32 v122, v200
	v_exp_f32_e32 v123, v201
	v_exp_f32_e32 v124, v202
	v_exp_f32_e32 v125, v203
	v_exp_f32_e32 v126, v204
	v_exp_f32_e32 v127, v205
	v_fma_f32 v206, -v120, v120, 1.0
	v_fma_f32 v207, -v121, v121, 1.0
	v_fma_f32 v208, -v122, v122, 1.0
	v_fma_f32 v209, -v123, v123, 1.0
	v_fma_f32 v210, -v124, v124, 1.0
	v_fma_f32 v211, -v125, v125, 1.0
	v_fma_f32 v212, -v126, v126, 1.0
	v_fma_f32 v213, -v127, v127, 1.0
	v_max_f32_e32 v206, 0xda24260, v206
	v_max_f32_e32 v207, 0xda24260, v207
	v_max_f32_e32 v208, 0xda24260, v208
	v_max_f32_e32 v209, 0xda24260, v209
	v_max_f32_e32 v210, 0xda24260, v210
	v_max_f32_e32 v211, 0xda24260, v211
	v_max_f32_e32 v212, 0xda24260, v212
	v_max_f32_e32 v213, 0xda24260, v213
	v_mul_f32_e32 v198, v214, v206
	v_mul_f32_e32 v199, v215, v207
	v_mul_f32_e32 v200, v216, v208
	v_mul_f32_e32 v201, v217, v209
	v_mul_f32_e32 v202, v218, v210
	v_mul_f32_e32 v203, v219, v211
	v_mul_f32_e32 v204, v220, v212
	v_mul_f32_e32 v205, v221, v213
	v_mul_f32_e32 v214, v214, v198
	v_mul_f32_e32 v215, v215, v199
	v_mul_f32_e32 v216, v216, v200
	v_mul_f32_e32 v217, v217, v201
	v_mul_f32_e32 v218, v218, v202
	v_mul_f32_e32 v219, v219, v203
	v_mul_f32_e32 v220, v220, v204
	v_mul_f32_e32 v221, v221, v205
	v_rsq_f32_e32 v214, v214
	v_mul_f32_e32 v222, v108, v206
	v_rsq_f32_e32 v215, v215
	v_mul_f32_e32 v223, v109, v207
	v_rsq_f32_e32 v216, v216
	v_mul_f32_e32 v224, v110, v208
	v_rsq_f32_e32 v217, v217
	v_mul_f32_e32 v225, v111, v209
	v_rsq_f32_e32 v218, v218
	v_mul_f32_e32 v226, v142, v210
	v_rsq_f32_e32 v219, v219
	v_mul_f32_e32 v227, v143, v211
	v_rsq_f32_e32 v220, v220
	v_mul_f32_e32 v228, v144, v212
	v_rsq_f32_e32 v221, v221
	v_mul_f32_e32 v229, v145, v213
	v_mul_f32_e32 v170, v222, v214
	v_mul_f32_e32 v171, v223, v215
	v_mul_f32_e32 v172, v224, v216
	v_mul_f32_e32 v173, v225, v217
	v_mul_f32_e32 v174, v226, v218
	v_mul_f32_e32 v175, v227, v219
	v_mul_f32_e32 v176, v228, v220
	v_mul_f32_e32 v177, v229, v221
	s_add_i32 s52, s4, 1
	s_sub_i32 s52, 31, s52
	s_lshl_b32 s52, s52, 12
	v_add_u32_e32 v197, s52, v184
	ds_read_u16 v206, v197 offset:0
	ds_read_u16 v207, v197 offset:64
	ds_read_u16 v208, v197 offset:128
	ds_read_u16 v209, v197 offset:192
	ds_read_u16 v210, v197 offset:256
	ds_read_u16 v211, v197 offset:320
	ds_read_u16 v212, v197 offset:384
	ds_read_u16 v213, v197 offset:448
	v_mov_b32_e32 v198, v177
	v_mov_b32_e32 v199, v127
	v_fma_f32 v198, v126, v198, v176
	v_mul_f32_e32 v199, v199, v126
	v_fma_f32 v198, v125, v198, v175
	v_mul_f32_e32 v199, v199, v125
	v_fma_f32 v198, v124, v198, v174
	v_mul_f32_e32 v199, v199, v124
	v_fma_f32 v198, v123, v198, v173
	v_mul_f32_e32 v199, v199, v123
	v_fma_f32 v198, v122, v198, v172
	v_mul_f32_e32 v199, v199, v122
	v_fma_f32 v198, v121, v198, v171
	v_mul_f32_e32 v199, v199, v121
	v_fma_f32 v198, v120, v198, v170
	v_mul_f32_e32 v199, v199, v120
	v_mov_b32_e32 v164, v199
	v_mov_b32_e32 v166, v199
	v_mov_b32_e32 v246, v198
	v_mov_b32_e32 v248, v198
	s_nop 1
	v_permlane32_swap_b32 v164, v166
	v_permlane32_swap_b32 v246, v248
	s_nop 1
	v_mov_b32_e32 v165, v164
	v_mov_b32_e32 v167, v166
	v_mov_b32_e32 v247, v246
	v_mov_b32_e32 v249, v248
	s_nop 1
	v_permlane16_swap_b32 v164, v165
	v_permlane16_swap_b32 v166, v167
	v_permlane16_swap_b32 v246, v247
	v_permlane16_swap_b32 v248, v249
	s_nop 1
	v_mov_b32_e32 v251, v249
	v_mov_b32_e32 v250, v167
	v_fma_f32 v251, v251, v166, v248
	v_mul_f32_e32 v250, v250, v166
	v_fma_f32 v251, v251, v165, v247
	v_mul_f32_e32 v250, v250, v165
	v_fma_f32 v251, v251, v164, v246
	v_mul_f32_e32 v250, v250, v164
	s_mov_b64 exec, s[10:11]
	ds_write_b64 v182, v[250:251] offset:1024
	s_mov_b64 exec, -1
	s_waitcnt lgkmcnt(0)
	s_barrier
	ds_read2_b64 v[4:7], v183 offset0:128 offset1:144
	s_add_i32 s52, s4, 1
	s_sub_i32 s52, 31, s52
	s_lshl_b32 s52, s52, 12
	v_add_u32_e32 v197, s52, v184
	s_waitcnt lgkmcnt(0)
	v_fma_f32 v198, v180, v6, v7
	v_cndmask_b32_e64 v199, v180, v198, s[24:25]
	v_fma_f32 v180, v198, v4, v5
	v_fma_f32 v200, v199, v167, v249
	v_cndmask_b32_e64 v199, v199, v200, s[16:17]
	v_fma_f32 v200, v199, v166, v248
	v_cndmask_b32_e64 v199, v199, v200, s[20:21]
	v_fma_f32 v200, v199, v165, v247
	v_cndmask_b32_e64 v199, v199, v200, s[22:23]
	v_fma_f32 v221, v127, v199, v177
	v_fma_f32 v220, v126, v221, v176
	v_fma_f32 v219, v125, v220, v175
	v_fma_f32 v218, v124, v219, v174
	v_fma_f32 v217, v123, v218, v173
	v_fma_f32 v216, v122, v217, v172
	v_fma_f32 v215, v121, v216, v171
	v_fma_f32 v214, v120, v215, v170
	s_waitcnt lgkmcnt(2)
	v_lshlrev_b32_e32 v206, 16, v206
	v_lshlrev_b32_e32 v207, 16, v207
	v_lshlrev_b32_e32 v208, 16, v208
	v_lshlrev_b32_e32 v209, 16, v209
	v_lshlrev_b32_e32 v210, 16, v210
	v_lshlrev_b32_e32 v211, 16, v211
	v_lshlrev_b32_e32 v212, 16, v212
	v_lshlrev_b32_e32 v213, 16, v213
	v_add_f32_e32 v214, v214, v206
	v_add_f32_e32 v215, v215, v207
	v_add_f32_e32 v216, v216, v208
	v_add_f32_e32 v217, v217, v209
	v_add_f32_e32 v218, v218, v210
	v_add_f32_e32 v219, v219, v211
	v_add_f32_e32 v220, v220, v212
	v_add_f32_e32 v221, v221, v213
	v_cvt_pk_bf16_f32 v206, v214, v215
	v_cvt_pk_bf16_f32 v208, v216, v217
	v_cvt_pk_bf16_f32 v210, v218, v219
	v_cvt_pk_bf16_f32 v212, v220, v221
	ds_write_b16 v197, v206 offset:0
	ds_write_b16_d16_hi v197, v206 offset:64
	ds_write_b16 v197, v208 offset:128
	ds_write_b16_d16_hi v197, v208 offset:192
	ds_write_b16 v197, v210 offset:256
	ds_write_b16_d16_hi v197, v210 offset:320
	ds_write_b16 v197, v212 offset:384
	ds_write_b16_d16_hi v197, v212 offset:448
	s_add_i32 s4, s4, 2
	s_cmp_lt_u32 s4, 32
	s_cbranch_scc1 .Lrec2_loopB_d1
	s_waitcnt lgkmcnt(0)
	s_barrier
	s_add_i32 s64, s4, -1
	s_sub_i32 s64, 31, s64
	s_mul_i32 s71, s64, 0x30000
	s_add_u32 s38, s60, s71
	s_addc_u32 s39, s61, 0
	s_lshl_b32 s64, s64, 12
	v_add_u32_e32 v136, s64, v195
	ds_read_b128 v[116:119], v136
	s_waitcnt vmcnt(3)
	s_waitcnt lgkmcnt(0)
	v_lshlrev_b32_e32 v136, 16, v116
	v_lshlrev_b32_e32 v137, 16, v8
	v_and_b32_e32 v168, 0xffff0000, v116
	v_and_b32_e32 v169, 0xffff0000, v8
	v_mul_f32_e32 v136, v136, v137
	v_mul_f32_e32 v168, v168, v169
	v_cvt_pk_bf16_f32 v116, v136, v168
	v_lshlrev_b32_e32 v136, 16, v117
	v_lshlrev_b32_e32 v137, 16, v9
	v_and_b32_e32 v168, 0xffff0000, v117
	v_and_b32_e32 v169, 0xffff0000, v9
	v_mul_f32_e32 v136, v136, v137
	v_mul_f32_e32 v168, v168, v169
	v_cvt_pk_bf16_f32 v117, v136, v168
	v_lshlrev_b32_e32 v136, 16, v118
	v_lshlrev_b32_e32 v137, 16, v10
	v_and_b32_e32 v168, 0xffff0000, v118
	v_and_b32_e32 v169, 0xffff0000, v10
	v_mul_f32_e32 v136, v136, v137
	v_mul_f32_e32 v168, v168, v169
	v_cvt_pk_bf16_f32 v118, v136, v168
	v_lshlrev_b32_e32 v136, 16, v119
	v_lshlrev_b32_e32 v137, 16, v11
	v_and_b32_e32 v168, 0xffff0000, v119
	v_and_b32_e32 v169, 0xffff0000, v11
	v_mul_f32_e32 v136, v136, v137
	v_mul_f32_e32 v168, v168, v169
	v_cvt_pk_bf16_f32 v119, v136, v168
	global_store_dwordx4 v255, v[116:119], s[38:39]
